# scan flush: y partial reads stay in flight across the next chunk's y-independent staging math; add/convert/store completes after it
# baseline (speedup 1.0000x reference)
; #define LAS __attribute__((address_space(3)))
; __device__ __forceinline__ unsigned cvt_pk_f16(float lo, float hi) { _Float16 a = (_Float16)lo, b = (_Float16)hi; return (unsigned)__builtin_bit_cast(unsigned short, a) | ((unsigned)__builtin_bit_cast(unsigned short, b) << 16); }
; __device__ __forceinline__ void scan_phase(const KP& P, LAS unsigned char* lds, const int tid, const int bx, const int G) {
;     ...
;             __syncthreads();
;             {
;                 const f32x4 y4 = *(const LAS f32x4*)(ybuf + tk * 64 + cg * 4);
;                 u32x2 w; w.x = cvt_pk_f16(y4.x, y4.y); w.y = cvt_pk_f16(y4.z, y4.w);
;                 *(u32x2*)(Yd + (size_t)scan_row(c, tk, d, b) * D + ch) = w;
;             }
;             if (c + 1 < NCH) SC_WRITE((c + 1) & 1, c + 1);
.LBB0_229:
	s_waitcnt lgkmcnt(0)
	s_barrier
	v_lshl_add_u32 v66, v52, 8, v57
	ds_read_b128 v[78:81], v66
	ds_read_b128 v[82:85], v66 offset:256
	ds_read_b128 v[66:69], v57 offset:16384
	ds_read_b128 v[74:77], v57 offset:24576
	s_cmp_lt_u32 s3, 8
	s_cselect_b64 vcc, -1, 0
	s_and_b64 s[0:1], vcc, exec
	s_cselect_b32 s0, 0xff, s80
	s_cselect_b32 s1, s31, s33
	v_lshl_add_u32 v70, s3, 5, v52
	v_add_u32_e32 v71, 0xffffff00, v70
	v_cndmask_b32_e32 v71, v71, v70, vcc
	v_sub_u32_e32 v70, s0, v70
	v_cndmask_b32_e64 v70, v70, v71, s[12:13]
	v_add_u32_e32 v70, s1, v70
	v_ashrrev_i32_e32 v71, 31, v70
	v_lshlrev_b64 v[70:71], 12, v[70:71]
	v_lshl_add_u64 v[70:71], v[32:33], 0, v[70:71]
	s_and_b64 vcc, exec, s[4:5]
	s_cbranch_vccnz .Lscan_flush_stage
	s_waitcnt lgkmcnt(0)
	v_pk_add_f32 v[78:79], v[78:79], v[82:83]
	v_pk_add_f32 v[80:81], v[80:81], v[84:85]
	v_cvt_f16_f32_e32 v86, v78
	v_cvt_f16_f32_sdwa v78, v79 dst_sel:WORD_1 dst_unused:UNUSED_PAD src0_sel:DWORD
	v_cvt_f16_f32_e32 v79, v80
	v_cvt_f16_f32_sdwa v80, v81 dst_sel:WORD_1 dst_unused:UNUSED_PAD src0_sel:DWORD
	v_or_b32_e32 v78, v78, v86
	v_or_b32_e32 v79, v80, v79
	global_store_dwordx2 v[70:71], v[78:79], off
	s_branch .LBB0_192
.Lscan_flush_stage:
	s_waitcnt vmcnt(0)
	v_cvt_f32_f16_sdwa v45, v30 dst_sel:DWORD dst_unused:UNUSED_PAD src0_sel:WORD_1
	v_cvt_f32_f16_e32 v44, v30
	v_cvt_f32_f16_sdwa v47, v31 dst_sel:DWORD dst_unused:UNUSED_PAD src0_sel:WORD_1
	v_cvt_f32_f16_e32 v46, v31
	v_lshlrev_b32_e32 v14, 16, v24
	v_pk_add_f32 v[18:19], v[44:45], -1.0 op_sel_hi:[1,0]
	v_and_b32_e32 v15, 0xffff0000, v24
	v_pk_add_f32 v[20:21], v[46:47], -1.0 op_sel_hi:[1,0]
	v_lshlrev_b32_e32 v16, 16, v25
	v_and_b32_e32 v17, 0xffff0000, v25
	v_pk_fma_f32 v[20:21], v[8:9], v[20:21], 1.0 op_sel_hi:[1,1,0]
	v_pk_fma_f32 v[18:19], v[6:7], v[18:19], 1.0 op_sel_hi:[1,1,0]
	v_pk_mul_f32 v[50:51], v[4:5], v[16:17]
	v_pk_mul_f32 v[48:49], v[2:3], v[14:15]
	v_pk_mul_f32 v[20:21], v[20:21], v[16:17]
	v_pk_mul_f32 v[18:19], v[18:19], v[14:15]
	v_lshlrev_b32_e32 v14, 16, v22
	v_and_b32_e32 v15, 0xffff0000, v22
	v_lshlrev_b32_e32 v16, 16, v23
	v_and_b32_e32 v17, 0xffff0000, v23
	v_pk_mul_f32 v[62:63], v[18:19], v[14:15]
	v_pk_mul_f32 v[64:65], v[20:21], v[16:17]
	v_mul_f32_e32 v0, v49, v49
	v_mul_f32_e32 v61, v51, v51
	v_pk_mul_f32 v[64:65], v[12:13], v[64:65]
	v_pk_mul_f32 v[62:63], v[10:11], v[62:63]
	v_fmac_f32_e32 v0, v48, v48
	v_fmac_f32_e32 v61, v50, v50
	v_add_f32_e32 v0, v0, v61
	v_add_f32_e32 v61, v62, v63
	v_add_f32_e32 v62, v64, v65
	v_add_f32_e32 v62, v61, v62
	v_add_f32_dpp v0, v0, v0 quad_perm:[1,0,3,2] row_mask:0xf bank_mask:0xf bound_ctrl:1
	s_nop 0
	v_add_f32_dpp v62, v62, v62 quad_perm:[1,0,3,2] row_mask:0xf bank_mask:0xf bound_ctrl:1
	v_add_f32_dpp v0, v0, v0 quad_perm:[2,3,0,1] row_mask:0xf bank_mask:0xf bound_ctrl:1
	s_nop 0
	v_add_f32_dpp v62, v62, v62 quad_perm:[2,3,0,1] row_mask:0xf bank_mask:0xf bound_ctrl:1
	v_add_f32_dpp v0, v0, v0 row_half_mirror row_mask:0xf bank_mask:0xf bound_ctrl:1
	s_nop 0
	v_add_f32_dpp v62, v62, v62 row_half_mirror row_mask:0xf bank_mask:0xf bound_ctrl:1
	v_mov_b32_dpp v61, v0 row_mirror row_mask:0xf bank_mask:0xf bound_ctrl:1
	s_nop 0
	v_mov_b32_dpp v63, v62 row_mirror row_mask:0xf bank_mask:0xf bound_ctrl:1
	s_waitcnt lgkmcnt(0)
	v_pk_add_f32 v[78:79], v[78:79], v[82:83]
	v_pk_add_f32 v[80:81], v[80:81], v[84:85]
	v_cvt_f16_f32_e32 v86, v78
	v_cvt_f16_f32_sdwa v78, v79 dst_sel:WORD_1 dst_unused:UNUSED_PAD src0_sel:DWORD
	v_cvt_f16_f32_e32 v79, v80
	v_cvt_f16_f32_sdwa v80, v81 dst_sel:WORD_1 dst_unused:UNUSED_PAD src0_sel:DWORD
	v_or_b32_e32 v78, v78, v86
	v_or_b32_e32 v79, v80, v79
	global_store_dwordx2 v[70:71], v[78:79], off
	s_and_saveexec_b64 s[0:1], s[6:7]
	s_cbranch_execz .LBB0_191
	s_cmp_lt_u32 s3, 7
	s_cselect_b64 vcc, -1, 0
	v_add_f32_e32 v64, v62, v63
	v_lshl_add_u32 v62, s2, 5, v52
	s_and_b64 s[4:5], vcc, exec
	v_add_u32_e32 v63, 0xffffff00, v62
	s_cselect_b32 s3, 0xff, s80
	v_cndmask_b32_e32 v63, v63, v62, vcc
	v_sub_u32_e32 v62, s3, v62
	s_cselect_b32 s4, s31, s33
	v_cndmask_b32_e64 v62, v62, v63, s[12:13]
	v_add_u32_e32 v62, s4, v62
	v_ashrrev_i32_e32 v63, 31, v62
	v_lshlrev_b64 v[62:63], 7, v[62:63]
	v_lshl_add_u64 v[62:63], v[34:35], 0, v[62:63]
	global_store_dword v[62:63], v64, off
	s_branch .LBB0_191
